# ResNorm epilogue: residual-stream stores issued after the row-sum flag (drain overlaps the exchange wait); norm/adaLN vector loads hoisted before the exchange
# speedup vs baseline: 1.0148x; 1.0148x over previous
.LBB0_832:
	s_lshr_b32 s26, s26, 2
	s_mulk_i32 s26, 0x1800
	s_lshl_b32 s38, s35, 5
	s_addk_i32 s26, 0x1800
	s_and_b64 s[2:3], s[2:3], exec
	s_cselect_b32 s26, 0, s26
	s_lshl_b32 s2, s62, 8
	s_or_b32 s2, s2, s38
	v_lshrrev_b32_e32 v128, 2, v192
	v_and_or_b32 v210, v128, 12, s2
	s_lshl_b64 s[2:3], s[26:27], 2
	v_readlane_b32 s38, v255, 12
	v_ashrrev_i32_e32 v161, 31, v160
	v_readlane_b32 s39, v255, 13
	s_add_u32 s38, s38, s2
	v_ashrrev_i32_e32 v211, 31, v210
	v_lshlrev_b64 v[130:131], 10, v[160:161]
	s_addc_u32 s39, s39, s3
	v_lshl_add_u64 v[206:207], v[130:131], 0, v[210:211]
	v_lshl_add_u64 v[128:129], v[210:211], 2, s[38:39]
	v_lshlrev_b64 v[150:151], 2, v[206:207]
	global_load_dwordx4 v[140:143], v[128:129], off
	global_load_dwordx4 v[136:139], v[128:129], off offset:64
	global_load_dwordx4 v[132:135], v[128:129], off offset:512
	s_nop 0
	global_load_dwordx4 v[128:131], v[128:129], off offset:576
	s_add_u32 s36, s76, s36
	v_cndmask_b32_e64 v152, 0, 1, s[20:21]
	s_addc_u32 s37, s77, s37
	v_readlane_b32 s52, v254, 49
	v_cmp_ne_u32_e64 s[38:39], 1, v152
	v_readlane_b32 s53, v254, 50
	v_readlane_b32 s20, v255, 16
	v_readlane_b32 s21, v255, 17
	s_lshl_b32 s26, s35, 2
	v_cmp_gt_u32_e64 s[40:41], 16, v224
	s_add_i32 s26, s26, 0
	s_movk_i32 s42, 0x210
	v_lshl_add_u64 v[208:209], s[36:37], 0, v[150:151]
	v_or_b32_e32 v184, 16, v160
	v_ashrrev_i32_e32 v185, 31, v184
	v_lshlrev_b64 v[250:251], 10, v[184:185]
	v_lshl_add_u64 v[202:203], v[250:251], 0, v[210:211]
	v_lshlrev_b64 v[250:251], 2, v[202:203]
	v_lshl_add_u64 v[204:205], s[36:37], 0, v[250:251]
	v_or_b32_e32 v184, 32, v160
	v_ashrrev_i32_e32 v185, 31, v184
	v_lshlrev_b64 v[250:251], 10, v[184:185]
	v_lshl_add_u64 v[198:199], v[250:251], 0, v[210:211]
	v_lshlrev_b64 v[250:251], 2, v[198:199]
	v_lshl_add_u64 v[200:201], s[36:37], 0, v[250:251]
	v_or_b32_e32 v184, 48, v160
	v_ashrrev_i32_e32 v185, 31, v184
	v_lshlrev_b64 v[250:251], 10, v[184:185]
	v_lshl_add_u64 v[194:195], v[250:251], 0, v[210:211]
	v_lshlrev_b64 v[250:251], 2, v[194:195]
	v_lshl_add_u64 v[196:197], s[36:37], 0, v[250:251]
	v_add_u32_e32 v184, 0x80, v160
	v_ashrrev_i32_e32 v185, 31, v184
	v_lshlrev_b64 v[250:251], 10, v[184:185]
	v_lshl_add_u64 v[174:175], v[250:251], 0, v[210:211]
	v_lshlrev_b64 v[250:251], 2, v[174:175]
	v_lshl_add_u64 v[176:177], s[36:37], 0, v[250:251]
	v_add_u32_e32 v184, 0x90, v160
	v_ashrrev_i32_e32 v185, 31, v184
	v_lshlrev_b64 v[250:251], 10, v[184:185]
	v_lshl_add_u64 v[170:171], v[250:251], 0, v[210:211]
	v_lshlrev_b64 v[250:251], 2, v[170:171]
	v_lshl_add_u64 v[172:173], s[36:37], 0, v[250:251]
	v_add_u32_e32 v184, 0xa0, v160
	v_ashrrev_i32_e32 v185, 31, v184
	v_lshlrev_b64 v[250:251], 10, v[184:185]
	v_lshl_add_u64 v[166:167], v[250:251], 0, v[210:211]
	v_lshlrev_b64 v[250:251], 2, v[166:167]
	v_lshl_add_u64 v[168:169], s[36:37], 0, v[250:251]
	v_add_u32_e32 v184, 0xb0, v160
	v_ashrrev_i32_e32 v185, 31, v184
	v_lshlrev_b64 v[250:251], 10, v[184:185]
	v_lshl_add_u64 v[162:163], v[250:251], 0, v[210:211]
	v_lshlrev_b64 v[250:251], 2, v[162:163]
	v_lshl_add_u64 v[164:165], s[36:37], 0, v[250:251]
	v_lshlrev_b64 v[250:251], 2, v[206:207]
	v_lshl_add_u64 v[212:213], s[0:1], 0, v[250:251]
	global_load_dwordx4 v[226:229], v[212:213], off
	global_load_dwordx4 v[230:233], v[212:213], off offset:64
	global_load_dwordx4 v[234:237], v[212:213], off offset:512
	global_load_dwordx4 v[238:241], v[212:213], off offset:576
	v_lshlrev_b64 v[250:251], 2, v[202:203]
	v_lshl_add_u64 v[212:213], s[0:1], 0, v[250:251]
	global_load_dwordx4 v[242:245], v[212:213], off
	global_load_dwordx4 v[246:249], v[212:213], off offset:64
	global_load_dwordx4 v[180:183], v[212:213], off offset:512
	global_load_dwordx4 v[188:191], v[212:213], off offset:576
	s_waitcnt vmcnt(4)
	v_pk_fma_f32 v[158:159], v[126:127], v[142:143], v[228:229]
	v_pk_fma_f32 v[156:157], v[124:125], v[140:141], v[226:227]
	v_pk_fma_f32 v[154:155], v[122:123], v[138:139], v[232:233]
	v_pk_fma_f32 v[152:153], v[120:121], v[136:137], v[230:231]
	v_pk_fma_f32 v[150:151], v[118:119], v[134:135], v[236:237]
	v_pk_fma_f32 v[148:149], v[116:117], v[132:133], v[234:235]
	v_pk_fma_f32 v[118:119], v[114:115], v[130:131], v[240:241]
	v_pk_fma_f32 v[116:117], v[112:113], v[128:129], v[238:239]
.Lrn_ns_0:
	v_lshlrev_b64 v[250:251], 2, v[198:199]
	v_lshl_add_u64 v[212:213], s[0:1], 0, v[250:251]
	global_load_dwordx4 v[226:229], v[212:213], off
	global_load_dwordx4 v[230:233], v[212:213], off offset:64
	global_load_dwordx4 v[234:237], v[212:213], off offset:512
	global_load_dwordx4 v[238:241], v[212:213], off offset:576
	v_and_b32_e32 v114, 64, v219
	v_xor_b32_e32 v113, 16, v219
	v_add_u32_e32 v114, 64, v114
	v_xor_b32_e32 v115, 32, v219
	v_cmp_lt_i32_e32 vcc, v113, v114
	s_nop 1
	v_cndmask_b32_e32 v113, v219, v113, vcc
	v_cmp_lt_i32_e32 vcc, v115, v114
	v_lshlrev_b32_e32 v120, 2, v113
	s_nop 0
	v_cndmask_b32_e32 v114, v219, v115, vcc
	v_lshlrev_b32_e32 v121, 2, v114
	v_mul_f32_e32 v186, v157, v157
	v_mul_f32_e32 v187, v159, v159
	v_fmac_f32_e32 v186, v156, v156
	v_fmac_f32_e32 v187, v158, v158
	v_add_f32_e32 v186, v186, v187
	v_mul_f32_e32 v187, v153, v153
	v_mul_f32_e32 v193, v155, v155
	v_fmac_f32_e32 v187, v152, v152
	v_fmac_f32_e32 v193, v154, v154
	v_add_f32_e32 v187, v187, v193
	v_add_f32_e32 v186, v186, v187
	v_mul_f32_e32 v187, v149, v149
	v_mul_f32_e32 v193, v151, v151
	v_fmac_f32_e32 v187, v148, v148
	v_fmac_f32_e32 v193, v150, v150
	v_add_f32_e32 v187, v187, v193
	v_add_f32_e32 v186, v186, v187
	v_mul_f32_e32 v187, v117, v117
	v_mul_f32_e32 v193, v119, v119
	v_fmac_f32_e32 v187, v116, v116
	v_fmac_f32_e32 v193, v118, v118
	v_add_f32_e32 v187, v187, v193
	v_add_f32_e32 v186, v186, v187
	ds_bpermute_b32 v225, v120, v186
	v_mov_b32_e32 v184, v160
	s_waitcnt lgkmcnt(0)
	v_add_f32_e32 v186, v186, v225
	ds_bpermute_b32 v225, v121, v186
	s_and_saveexec_b64 s[46:47], s[40:41]
	s_cbranch_execz .Lrn_nw_0
	v_lshl_add_u32 v187, v184, 4, s26
	s_waitcnt lgkmcnt(0)
	v_add_f32_e32 v186, v186, v225
	ds_write_b32 v187, v186
.Lrn_nw_0:
	s_or_b64 exec, exec, s[46:47]
	s_waitcnt lgkmcnt(0)
	s_waitcnt vmcnt(4)
	v_pk_fma_f32 v[146:147], v[110:111], v[142:143], v[244:245]
	v_pk_fma_f32 v[144:145], v[108:109], v[140:141], v[242:243]
	v_pk_fma_f32 v[126:127], v[106:107], v[138:139], v[248:249]
	v_pk_fma_f32 v[124:125], v[104:105], v[136:137], v[246:247]
	v_pk_fma_f32 v[106:107], v[102:103], v[134:135], v[182:183]
	v_pk_fma_f32 v[104:105], v[100:101], v[132:133], v[180:181]
	v_pk_fma_f32 v[94:95], v[94:95], v[130:131], v[190:191]
	v_pk_fma_f32 v[92:93], v[92:93], v[128:129], v[188:189]

.Lrn_nw_1:
	s_or_b64 exec, exec, s[46:47]
	s_waitcnt lgkmcnt(0)
	s_waitcnt vmcnt(4)
	v_pk_fma_f32 v[98:99], v[98:99], v[142:143], v[228:229]
	v_pk_fma_f32 v[96:97], v[96:97], v[140:141], v[226:227]
	v_pk_fma_f32 v[90:91], v[90:91], v[138:139], v[232:233]
	v_pk_fma_f32 v[88:89], v[88:89], v[136:137], v[230:231]
	v_pk_fma_f32 v[86:87], v[86:87], v[134:135], v[236:237]
	v_pk_fma_f32 v[84:85], v[84:85], v[132:133], v[234:235]
	v_pk_fma_f32 v[78:79], v[78:79], v[130:131], v[240:241]
	v_pk_fma_f32 v[76:77], v[76:77], v[128:129], v[238:239]

.Lrn_nw_2:
	s_or_b64 exec, exec, s[46:47]
	s_waitcnt lgkmcnt(0)
	s_waitcnt vmcnt(4)
	v_pk_fma_f32 v[82:83], v[82:83], v[142:143], v[244:245]
	v_pk_fma_f32 v[80:81], v[80:81], v[140:141], v[242:243]
	v_pk_fma_f32 v[74:75], v[74:75], v[138:139], v[248:249]
	v_pk_fma_f32 v[72:73], v[72:73], v[136:137], v[246:247]
	v_pk_fma_f32 v[70:71], v[70:71], v[134:135], v[182:183]
	v_pk_fma_f32 v[68:69], v[68:69], v[132:133], v[180:181]
	v_pk_fma_f32 v[62:63], v[62:63], v[130:131], v[190:191]
	v_pk_fma_f32 v[60:61], v[60:61], v[128:129], v[188:189]

.Lrn_nw_3:
	s_or_b64 exec, exec, s[46:47]
	s_waitcnt lgkmcnt(0)
	s_waitcnt vmcnt(4)
	v_pk_fma_f32 v[66:67], v[66:67], v[142:143], v[228:229]
	v_pk_fma_f32 v[64:65], v[64:65], v[140:141], v[226:227]
	v_pk_fma_f32 v[58:59], v[58:59], v[138:139], v[232:233]
	v_pk_fma_f32 v[56:57], v[56:57], v[136:137], v[230:231]
	v_pk_fma_f32 v[54:55], v[54:55], v[134:135], v[236:237]
	v_pk_fma_f32 v[52:53], v[52:53], v[132:133], v[234:235]
	v_pk_fma_f32 v[46:47], v[46:47], v[130:131], v[240:241]
	v_pk_fma_f32 v[44:45], v[44:45], v[128:129], v[238:239]

.Lrn_nw_4:
	s_or_b64 exec, exec, s[46:47]
	s_waitcnt lgkmcnt(0)
	s_waitcnt vmcnt(4)
	v_pk_fma_f32 v[50:51], v[50:51], v[142:143], v[244:245]
	v_pk_fma_f32 v[48:49], v[48:49], v[140:141], v[242:243]
	v_pk_fma_f32 v[42:43], v[42:43], v[138:139], v[248:249]
	v_pk_fma_f32 v[40:41], v[40:41], v[136:137], v[246:247]
	v_pk_fma_f32 v[38:39], v[38:39], v[134:135], v[182:183]
	v_pk_fma_f32 v[36:37], v[36:37], v[132:133], v[180:181]
	v_pk_fma_f32 v[34:35], v[34:35], v[130:131], v[190:191]
	v_pk_fma_f32 v[32:33], v[32:33], v[128:129], v[188:189]

.Lrn_nw_5:
	s_or_b64 exec, exec, s[46:47]
	s_waitcnt lgkmcnt(0)
	s_waitcnt vmcnt(4)
	v_pk_fma_f32 v[30:31], v[30:31], v[142:143], v[228:229]
	v_pk_fma_f32 v[28:29], v[28:29], v[140:141], v[226:227]
	v_pk_fma_f32 v[26:27], v[26:27], v[138:139], v[232:233]
	v_pk_fma_f32 v[24:25], v[24:25], v[136:137], v[230:231]
	v_pk_fma_f32 v[22:23], v[22:23], v[134:135], v[236:237]
	v_pk_fma_f32 v[20:21], v[20:21], v[132:133], v[234:235]
	v_pk_fma_f32 v[18:19], v[18:19], v[130:131], v[240:241]
	v_pk_fma_f32 v[16:17], v[16:17], v[128:129], v[238:239]

.Lrn_nw_6:
	s_or_b64 exec, exec, s[46:47]
	s_waitcnt lgkmcnt(0)
	s_waitcnt vmcnt(0)
	v_pk_fma_f32 v[14:15], v[14:15], v[142:143], v[244:245]
	v_pk_fma_f32 v[12:13], v[12:13], v[140:141], v[242:243]
	v_pk_fma_f32 v[10:11], v[10:11], v[138:139], v[248:249]
	v_pk_fma_f32 v[8:9], v[8:9], v[136:137], v[246:247]
	v_pk_fma_f32 v[6:7], v[6:7], v[134:135], v[182:183]
	v_pk_fma_f32 v[4:5], v[4:5], v[132:133], v[180:181]
	v_pk_fma_f32 v[2:3], v[2:3], v[130:131], v[190:191]
	v_pk_fma_f32 v[0:1], v[0:1], v[128:129], v[188:189]

.Lrn_nw_7:
	s_or_b64 exec, exec, s[0:1]
	s_waitcnt lgkmcnt(0)
	v_mov_b64_e32 v[180:181], 0x240
	v_mov_b64_e32 v[182:183], 0x23f
	v_mov_b64_e32 v[186:187], 0x41f
	v_mov_b64_e32 v[188:189], 0xc0
	v_mov_b64_e32 v[190:191], 0xbf
	s_waitcnt lgkmcnt(0)
	s_barrier
	v_lshlrev_b32_e32 v193, 2, v210
	global_load_dwordx4 v[128:131], v193, s[58:59]
	global_load_dwordx4 v[136:139], v193, s[58:59] offset:64
	global_load_dwordx4 v[120:123], v193, s[58:59] offset:512
	global_load_dwordx4 v[112:115], v193, s[58:59] offset:576
	s_and_b64 vcc, exec, s[38:39]
	s_cbranch_vccnz .Lmh_nomod_a
	v_readlane_b32 s98, v255, 14
	v_readlane_b32 s99, v255, 15
	s_add_u32 s100, s44, s2
	s_addc_u32 s101, s45, s3
	s_add_u32 s98, s98, s2
	s_addc_u32 s99, s99, s3
	global_load_dwordx4 v[140:143], v193, s[100:101]
	global_load_dwordx4 v[108:111], v193, s[100:101] offset:64
	global_load_dwordx4 v[132:135], v193, s[100:101] offset:512
	global_load_dwordx4 v[100:103], v193, s[100:101] offset:576
	global_load_dwordx4 v[226:229], v193, s[98:99]
	global_load_dwordx4 v[230:233], v193, s[98:99] offset:64
	global_load_dwordx4 v[234:237], v193, s[98:99] offset:512
	global_load_dwordx4 v[238:241], v193, s[98:99] offset:576
.Lmh_nomod_a:
	v_and_b32_e32 v242, 31, v192
	s_waitcnt lgkmcnt(0)
	v_lshl_or_b32 v161, s34, 5, v242
	v_cmp_gt_u32_e64 s[0:1], 32, v224
	v_lshl_add_u32 v242, s22, 8, v161
	s_and_saveexec_b64 s[36:37], s[0:1]
	s_cbranch_execz .LBB0_914

	v_lshl_add_u32 v243, v161, 4, 0
	ds_read_b128 v[248:251], v243
	v_ashrrev_i32_e32 v243, 31, v242
	s_ashr_i32 s63, s62, 31
	s_waitcnt lgkmcnt(0)
	v_mov_b32_e32 v184, v249
	v_mov_b32_e32 v185, v250
	v_mov_b32_e32 v249, v251
	v_pk_add_f32 v[248:249], v[184:185], v[248:249]
	v_lshl_add_u64 v[250:251], v[242:243], 4, s[60:61]
	v_pk_add_f32 v[248:249], v[248:249], v[248:249] op_sel:[0,1] op_sel_hi:[1,0]
	v_lshl_add_u64 v[250:251], s[62:63], 2, v[250:251]
	global_store_dword v[250:251], v248, off sc1
.LBB0_914:
	s_or_b64 exec, exec, s[36:37]
	s_waitcnt vmcnt(0)
	v_cmp_eq_u32_e32 vcc, 0, v224
	s_and_saveexec_b64 s[36:37], vcc
	s_cbranch_execz .LBB0_917

	s_mov_b64 s[40:41], exec
	v_mbcnt_lo_u32_b32 v243, s40, 0
	v_mbcnt_hi_u32_b32 v243, s41, v243
	v_cmp_eq_u32_e32 vcc, 0, v243
	s_and_b64 s[34:35], exec, vcc
	s_mov_b64 exec, s[34:35]
	s_cbranch_execz .LBB0_917

	s_lshl_b32 s34, s22, 4
	s_ashr_i32 s35, s34, 31
	s_lshl_b64 s[34:35], s[34:35], 2
	s_add_u32 s34, s80, s34
	s_addc_u32 s35, s81, s35
	s_bcnt1_i32_b64 s26, s[40:41]
	v_mov_b32_e32 v243, s26
	global_atomic_add v179, v243, s[34:35]
.LBB0_917:
	s_or_b64 exec, exec, s[36:37]
	s_and_b64 vcc, exec, s[38:39]
	s_cbranch_vccnz .Lxs_skip
	global_store_dwordx4 v[208:209], v[156:159], off
	global_store_dwordx4 v[208:209], v[152:155], off offset:64
	global_store_dwordx4 v[208:209], v[148:151], off offset:512
	global_store_dwordx4 v[208:209], v[116:119], off offset:576
	global_store_dwordx4 v[204:205], v[144:147], off
	global_store_dwordx4 v[204:205], v[124:127], off offset:64
	global_store_dwordx4 v[204:205], v[104:107], off offset:512
	global_store_dwordx4 v[204:205], v[92:95], off offset:576
	global_store_dwordx4 v[200:201], v[96:99], off
	global_store_dwordx4 v[200:201], v[88:91], off offset:64
	global_store_dwordx4 v[200:201], v[84:87], off offset:512
	global_store_dwordx4 v[200:201], v[76:79], off offset:576
	global_store_dwordx4 v[196:197], v[80:83], off
	global_store_dwordx4 v[196:197], v[72:75], off offset:64
	global_store_dwordx4 v[196:197], v[68:71], off offset:512
	global_store_dwordx4 v[196:197], v[60:63], off offset:576
	global_store_dwordx4 v[176:177], v[64:67], off
	global_store_dwordx4 v[176:177], v[56:59], off offset:64
	global_store_dwordx4 v[176:177], v[52:55], off offset:512
	global_store_dwordx4 v[176:177], v[44:47], off offset:576
	global_store_dwordx4 v[172:173], v[48:51], off
	global_store_dwordx4 v[172:173], v[40:43], off offset:64
	global_store_dwordx4 v[172:173], v[36:39], off offset:512
	global_store_dwordx4 v[172:173], v[32:35], off offset:576
	global_store_dwordx4 v[168:169], v[28:31], off
	global_store_dwordx4 v[168:169], v[24:27], off offset:64
	global_store_dwordx4 v[168:169], v[20:23], off offset:512
	global_store_dwordx4 v[168:169], v[16:19], off offset:576
	global_store_dwordx4 v[164:165], v[12:15], off
	global_store_dwordx4 v[164:165], v[8:11], off offset:64
	global_store_dwordx4 v[164:165], v[4:7], off offset:512
	global_store_dwordx4 v[164:165], v[0:3], off offset:576
.Lxs_skip:
	s_cmp_gt_u32 s33, 63
	s_cbranch_scc1 .LBB0_927

	s_lshl_b32 s34, s22, 4
	s_ashr_i32 s35, s34, 31
	s_lshl_b64 s[34:35], s[34:35], 2
	s_add_u32 s36, s80, s34
	s_addc_u32 s37, s81, s35
	s_mov_b32 s26, 0x400001
	s_branch .LBB0_920

.LBB0_920:

	global_load_dword v243, v179, s[36:37] sc1
	s_mov_b64 s[40:41], -1
	s_waitcnt vmcnt(0)
	v_readfirstlane_b32 s33, v243
	s_cmp_gt_u32 s33, 31
	s_cbranch_scc1 .LBB0_919

	s_sleep 2
	global_load_dword v243, v179, s[36:37] sc1
	s_waitcnt vmcnt(0)
	v_readfirstlane_b32 s33, v243
	s_cmp_lt_u32 s33, 32
	s_cbranch_scc0 .LBB0_919

	s_sleep 2
	global_load_dword v243, v179, s[36:37] sc1
	s_waitcnt vmcnt(0)
	v_readfirstlane_b32 s33, v243
	s_cmp_lt_u32 s33, 32
	s_cbranch_scc0 .LBB0_919

	s_sleep 2
	global_load_dword v243, v179, s[36:37] sc1
	s_waitcnt vmcnt(0)
	v_readfirstlane_b32 s33, v243
	s_cmp_lt_u32 s33, 32
	s_cbranch_scc0 .LBB0_919

	s_sleep 2
	global_load_dword v243, v179, s[36:37] sc1
	s_waitcnt vmcnt(0)
	v_readfirstlane_b32 s33, v243
	s_cmp_lt_u32 s33, 32
	s_cbranch_scc0 .LBB0_919

	s_add_i32 s26, s26, -5
	s_cmp_eq_u32 s26, 0
	s_cselect_b64 s[40:41], -1, 0
	s_sleep 2
	s_branch .LBB0_919

.LBB0_927:
	s_waitcnt vmcnt(0) lgkmcnt(0)
	s_barrier
	s_and_saveexec_b64 s[36:37], s[0:1]
	s_cbranch_execz .LBB0_929

	v_ashrrev_i32_e32 v243, 31, v242
	v_lshl_add_u64 v[242:243], v[242:243], 4, s[60:61]
	global_load_dword v178, v[242:243], off sc1
	global_load_dword v248, v[242:243], off offset:4 sc1
	global_load_dword v249, v[242:243], off offset:8 sc1
	s_nop 0
	global_load_dword v242, v[242:243], off offset:12 sc1
	s_mov_b32 s0, 0xf800000
	s_waitcnt vmcnt(3)
	v_add_f32_e32 v243, 0, v178
	s_waitcnt vmcnt(2)
	v_add_f32_e32 v243, v243, v248
	s_waitcnt vmcnt(1)
	v_add_f32_e32 v243, v243, v249
	s_waitcnt vmcnt(0)
	v_add_f32_e32 v242, v243, v242
	v_fmamk_f32 v242, v242, 0x3a800000, v217
	v_mul_f32_e32 v243, 0x4f800000, v242
	v_cmp_gt_f32_e32 vcc, s0, v242
	s_nop 1
	v_cndmask_b32_e32 v242, v242, v243, vcc
	v_sqrt_f32_e32 v243, v242
	s_nop 0
	v_add_u32_e32 v178, -1, v243
	v_add_u32_e32 v248, 1, v243
	v_fma_f32 v249, -v178, v243, v242
	v_fma_f32 v250, -v248, v243, v242
	v_cmp_ge_f32_e64 s[0:1], 0, v249
	s_nop 1
	v_cndmask_b32_e64 v243, v243, v178, s[0:1]
	v_cmp_lt_f32_e64 s[0:1], 0, v250
	s_nop 1
	v_cndmask_b32_e64 v243, v243, v248, s[0:1]
	v_mul_f32_e32 v178, 0x37800000, v243
	v_cndmask_b32_e32 v243, v243, v178, vcc
	v_cmp_class_f32_e32 vcc, v242, v218
	s_nop 1
	v_cndmask_b32_e32 v242, v243, v242, vcc
	v_div_scale_f32 v243, s[0:1], v242, v242, 1.0
	v_rcp_f32_e32 v178, v243
	v_div_scale_f32 v248, vcc, 1.0, v242, 1.0
	v_fma_f32 v249, -v243, v178, 1.0
	v_fmac_f32_e32 v178, v249, v178
	v_mul_f32_e32 v249, v248, v178
	v_fma_f32 v250, -v243, v249, v248
	v_fmac_f32_e32 v249, v250, v178
	v_fma_f32 v243, -v243, v249, v248
	v_div_fmas_f32 v243, v243, v178, v249
	v_div_fixup_f32 v242, v243, v242, 1.0
	v_lshl_add_u32 v243, v161, 2, 0
	ds_write_b32 v243, v242 offset:8192
.LBB0_929:
	s_or_b64 exec, exec, s[36:37]
	s_waitcnt vmcnt(0) lgkmcnt(0)
	s_barrier
	s_and_b64 vcc, exec, s[38:39]
	s_cbranch_vccnz .Lmh_nomod_b
	v_pk_add_f32 v[226:227], v[226:227], 1.0 op_sel_hi:[1,0]
	v_pk_add_f32 v[228:229], v[228:229], 1.0 op_sel_hi:[1,0]
	v_pk_add_f32 v[230:231], v[230:231], 1.0 op_sel_hi:[1,0]
	v_pk_add_f32 v[232:233], v[232:233], 1.0 op_sel_hi:[1,0]
	v_pk_add_f32 v[234:235], v[234:235], 1.0 op_sel_hi:[1,0]
	v_pk_add_f32 v[236:237], v[236:237], 1.0 op_sel_hi:[1,0]
	v_pk_add_f32 v[238:239], v[238:239], 1.0 op_sel_hi:[1,0]
	v_pk_add_f32 v[240:241], v[240:241], 1.0 op_sel_hi:[1,0]
	v_pk_mul_f32 v[128:129], v[128:129], v[226:227]
	v_pk_mul_f32 v[130:131], v[130:131], v[228:229]
	v_pk_mul_f32 v[136:137], v[136:137], v[230:231]
	v_pk_mul_f32 v[138:139], v[138:139], v[232:233]
	v_pk_mul_f32 v[120:121], v[120:121], v[234:235]
	v_pk_mul_f32 v[122:123], v[122:123], v[236:237]
	v_pk_mul_f32 v[112:113], v[112:113], v[238:239]
	v_pk_mul_f32 v[114:115], v[114:115], v[240:241]
	s_branch .LBB0_938
.Lmh_nomod_b:
	v_mov_b32_e32 v140, 0
	v_mov_b32_e32 v141, 0
	v_mov_b32_e32 v142, 0
	v_mov_b32_e32 v143, 0
	v_mov_b32_e32 v108, 0
	v_mov_b32_e32 v109, 0
	v_mov_b32_e32 v110, 0
	v_mov_b32_e32 v111, 0
	v_mov_b32_e32 v132, 0
	v_mov_b32_e32 v133, 0
	v_mov_b32_e32 v134, 0
	v_mov_b32_e32 v135, 0
	v_mov_b32_e32 v100, 0
	v_mov_b32_e32 v101, 0
	v_mov_b32_e32 v102, 0
	v_mov_b32_e32 v103, 0
